# kernel entry: all kernel-argument scalar loads issued together (one scalar round trip instead of two)
# speedup vs baseline: 1.0124x; 1.0124x over previous
_Z6mk_fwd4Args:
	s_load_dwordx2 s[34:35], s[0:1], 0xa0
	s_load_dword s33, s[0:1], 0xb8
	s_load_dwordx8 s[72:79], s[0:1], 0x80
	s_load_dwordx2 s[56:57], s[0:1], 0xa8
	s_load_dwordx16 s[36:51], s[0:1], 0x0
	s_load_dwordx16 s[8:23], s[0:1], 0x40
	v_readfirstlane_b32 s60, v0
	s_mov_b32 s89, s2
	s_waitcnt lgkmcnt(0)
	v_writelane_b32 v250, s72, 0
	s_nop 1
	v_writelane_b32 v250, s73, 1
	v_writelane_b32 v250, s74, 2
	v_writelane_b32 v250, s75, 3
	v_writelane_b32 v250, s76, 4
	v_writelane_b32 v250, s77, 5
	v_writelane_b32 v250, s78, 6
	v_writelane_b32 v250, s79, 7
	s_add_u32 s4, s0, 0xb8
	s_addc_u32 s5, s1, 0
	s_and_b32 s3, s33, 7
	v_writelane_b32 v250, s4, 8
	s_cmp_lg_u32 s3, 0
	s_nop 0
	v_writelane_b32 v250, s5, 9
	s_cbranch_scc1 .LBB0_2
	s_ashr_i32 s4, s2, 31
	s_lshr_b32 s4, s4, 29
	s_add_i32 s4, s2, s4
	s_and_b32 s5, s4, -8
	s_ashr_i32 s3, s33, 3
	s_sub_i32 s5, s2, s5
	s_mul_i32 s3, s3, s5
	s_ashr_i32 s4, s4, 3
	s_add_i32 s89, s3, s4

.LBB0_4:
	v_cmp_gt_u32_e64 s[4:5], s3, v0
	s_and_saveexec_b64 s[6:7], s[4:5]
	v_lshl_add_u32 v1, v0, 2, 0
	v_add_u32_e32 v1, 0x27c00, v1
	v_mov_b32_e32 v2, 0
	ds_write_b32 v1, v2
	s_or_b64 exec, exec, s[6:7]
	s_add_u32 s0, s34, 0x4000
	s_addc_u32 s1, s35, 0
	v_writelane_b32 v250, s0, 10
	s_waitcnt lgkmcnt(0)
	s_barrier
	v_writelane_b32 v250, s1, 11
	s_getreg_b32 s0, hwreg(HW_REG_XCC_ID, 0, 4)
	s_and_b32 s0, s0, 15
	v_cmp_eq_u32_e64 s[58:59], 0, v0
	v_writelane_b32 v250, s0, 12
	s_and_saveexec_b64 s[6:7], s[58:59]
	s_cbranch_execz .LBB0_9
	s_mov_b64 s[52:53], exec
	v_mbcnt_lo_u32_b32 v1, s52, 0
	v_mbcnt_hi_u32_b32 v1, s53, v1
	v_cmp_eq_u32_e32 vcc, 0, v1
	s_and_b64 s[0:1], exec, vcc
	s_mov_b64 exec, s[0:1]
	s_cbranch_execz .LBB0_9
	v_readlane_b32 s0, v250, 12
	s_lshl_b32 s0, s0, 8
	s_bcnt1_i32_b64 s1, s[52:53]
	v_mov_b32_e32 v1, s0
	v_mov_b32_e32 v2, s1
	v_readlane_b32 s0, v250, 10
	v_readlane_b32 s1, v250, 11
	s_nop 4
	global_atomic_add v1, v2, s[0:1] offset:1024
